# GEMM mainloops: loop-top SALU block moved behind the first 8 ds_reads of the load phase (loop-edge edit)
# speedup vs baseline: 1.0048x; 1.0048x over previous
; #define PG8_STAGE(bufoff, gbase, voff) do { _Pragma("unroll") for (int _i = 0; _i < 2; ++_i) \
;         __builtin_amdgcn_global_load_lds((const unsigned*)((const char*)(gbase) + (voff)[_i]), (LAS unsigned*)(lds + (bufoff) + ldsw + _i * 8192), 16, 0, 0); } while (0)
; #define PG8_LDA(dst, b, h) do { _Pragma("unroll") for (int m = 0; m < 4; ++m) _Pragma("unroll") for (int k = 0; k < 2; ++k) dst[m][k] = *(const LAS bf16x8*)(lds + PG8_SA(b, h) + aoff + m * 2048 + k * 1024); } while (0)
; #define PG8_LDB(dst, b, h) do { _Pragma("unroll") for (int n = 0; n < 2; ++n) _Pragma("unroll") for (int k = 0; k < 2; ++k) dst[n][k] = *(const LAS bf16x8*)(lds + PG8_SB(b, h) + boff + n * 2048 + k * 1024); } while (0)
; #define PG8_MMA(ai, bj, At, Bt) do { __builtin_amdgcn_s_setprio(1); _Pragma("unroll") for (int m = 0; m < 4; ++m) _Pragma("unroll") for (int n = 0; n < 2; ++n) _Pragma("unroll") for (int k = 0; k < 2; ++k) \
;         acc[ai][bj][m][n] = __builtin_amdgcn_mfma_f32_16x16x32_bf16(Bt[n][k], At[m][k], acc[ai][bj][m][n], 0, 0, 0); __builtin_amdgcn_s_setprio(0); } while (0)
; #define PG8_WAIT_V(n) asm volatile("s_waitcnt vmcnt(" #n ")" ::: "memory")
; #define PG8_WAIT_L(n) asm volatile("s_waitcnt lgkmcnt(" #n ")" ::: "memory")
; #define PG8_BAR __builtin_amdgcn_s_barrier()
; #define PG8_SCHED __builtin_amdgcn_sched_barrier(0)
; template <class Epi>
; __device__ __forceinline__ void gemm_phase(LAS unsigned char* lds, const Gemm g, const StaticOrder& S, const Epi& E) {
;     ...
;         for (int t = 0; t < nt; t += 2) {
;             const bool last = (t == nt - 2);
;             const char* a1 = cA + (size_t)(t + 1) * kstep;
;             const char* a2 = last ? nA : cA + (size_t)(t + 2) * kstep; const char* b2 = last ? nB : cB + (size_t)(t + 2) * kstep;
;             const char* a3 = a2 + kstep; const char* b3 = b2 + kstep;
;             PG8_LDB(B0, 0, 0); PG8_LDB(B1, 0, 1); PG8_SCHED; PG8_LDA(At, 0, 0); PG8_STAGE(PG8_SA(1, 1), a1 + hstepA, voffA);
;             PG8_WAIT_V(8); PG8_WAIT_L(0); PG8_BAR; PG8_MMA(0, 0, At, B0); PG8_MMA(0, 1, At, B1); PG8_BAR; PG8_SCHED;
;             PG8_LDA(At, 0, 1); PG8_STAGE(PG8_SB(0, 0), b2, voffB); PG8_STAGE(PG8_SB(0, 1), b2 + hstepB, voffB); PG8_STAGE(PG8_SA(0, 0), a2, voffA);
;             PG8_WAIT_V(8); PG8_WAIT_L(0); PG8_BAR; PG8_MMA(1, 0, At, B0); PG8_MMA(1, 1, At, B1); PG8_BAR; PG8_SCHED;
.LBB0_233:
	s_add_i32 s52, 0, 0x10000
	v_add_u32_e32 v155, s52, v145
	s_add_i32 s53, 0, 0x14000
	ds_read_b128 v[140:143], v155
	ds_read_b128 v[156:159], v155 offset:1024
	ds_read_b128 v[166:169], v155 offset:2048
	ds_read_b128 v[170:173], v155 offset:3072
	v_add_u32_e32 v155, s53, v145
	ds_read_b128 v[174:177], v155
	ds_read_b128 v[178:181], v155 offset:1024
	ds_read_b128 v[194:197], v155 offset:2048
	ds_read_b128 v[198:201], v155 offset:3072
	s_add_i32 s83, s26, 2
	s_add_u32 vcc_lo, s12, 0x80
	s_addc_u32 s27, s13, 0
	s_cmp_eq_u32 s61, s26
	s_cselect_b32 s27, s3, s27
	s_cselect_b32 s26, s2, vcc_lo
	s_cselect_b32 vcc_hi, s25, s82
	s_cselect_b32 vcc_lo, s24, s57
	s_add_i32 m0, s30, 0xc000
	ds_read_b128 v[202:205], v154
	global_load_lds_dwordx4 v136, s[12:13]
	s_add_i32 m0, s30, 0xe000
	ds_read_b128 v[206:209], v154 offset:1024
	global_load_lds_dwordx4 v138, s[12:13]
	ds_read_b128 v[210:213], v154 offset:2048
	ds_read_b128 v[214:217], v154 offset:3072
	ds_read_b128 v[218:221], v154 offset:4096
	ds_read_b128 v[222:225], v154 offset:5120
	ds_read_b128 v[226:229], v154 offset:6144
	ds_read_b128 v[234:237], v154 offset:7168
	s_waitcnt vmcnt(8)
	s_waitcnt lgkmcnt(0)
	s_setprio 1
	s_barrier
	v_mfma_f32_16x16x32_bf16 v[126:129], v[140:143], v[202:205], v[126:129]
	v_mfma_f32_16x16x32_bf16 v[122:125], v[166:169], v[202:205], v[122:125]
	v_mfma_f32_16x16x32_bf16 v[110:113], v[140:143], v[210:213], v[110:113]
	v_mfma_f32_16x16x32_bf16 v[106:109], v[166:169], v[210:213], v[106:109]
	v_mfma_f32_16x16x32_bf16 v[94:97], v[140:143], v[218:221], v[94:97]
	v_mfma_f32_16x16x32_bf16 v[90:93], v[166:169], v[218:221], v[90:93]
	v_mfma_f32_16x16x32_bf16 v[78:81], v[140:143], v[226:229], v[78:81]
	v_mfma_f32_16x16x32_bf16 v[74:77], v[166:169], v[226:229], v[74:77]
	v_mfma_f32_16x16x32_bf16 v[126:129], v[156:159], v[206:209], v[126:129]
	v_mfma_f32_16x16x32_bf16 v[122:125], v[170:173], v[206:209], v[122:125]
	v_mfma_f32_16x16x32_bf16 v[110:113], v[156:159], v[214:217], v[110:113]
	v_mfma_f32_16x16x32_bf16 v[106:109], v[170:173], v[214:217], v[106:109]
	v_mfma_f32_16x16x32_bf16 v[94:97], v[156:159], v[222:225], v[94:97]
	v_mfma_f32_16x16x32_bf16 v[90:93], v[170:173], v[222:225], v[90:93]
	v_mfma_f32_16x16x32_bf16 v[78:81], v[156:159], v[234:237], v[78:81]
	v_mfma_f32_16x16x32_bf16 v[74:77], v[170:173], v[234:237], v[74:77]
	v_mfma_f32_16x16x32_bf16 v[118:121], v[174:177], v[202:205], v[118:121]
	v_mfma_f32_16x16x32_bf16 v[114:117], v[194:197], v[202:205], v[114:117]
	v_mfma_f32_16x16x32_bf16 v[102:105], v[174:177], v[210:213], v[102:105]
	v_mfma_f32_16x16x32_bf16 v[98:101], v[194:197], v[210:213], v[98:101]
	v_mfma_f32_16x16x32_bf16 v[86:89], v[174:177], v[218:221], v[86:89]
	v_mfma_f32_16x16x32_bf16 v[82:85], v[194:197], v[218:221], v[82:85]
	v_mfma_f32_16x16x32_bf16 v[70:73], v[174:177], v[226:229], v[70:73]
	v_mfma_f32_16x16x32_bf16 v[66:69], v[194:197], v[226:229], v[66:69]
	v_mfma_f32_16x16x32_bf16 v[118:121], v[178:181], v[206:209], v[118:121]
	v_mfma_f32_16x16x32_bf16 v[114:117], v[198:201], v[206:209], v[114:117]
	v_mfma_f32_16x16x32_bf16 v[102:105], v[178:181], v[214:217], v[102:105]
	v_mfma_f32_16x16x32_bf16 v[98:101], v[198:201], v[214:217], v[98:101]
	v_mfma_f32_16x16x32_bf16 v[86:89], v[178:181], v[222:225], v[86:89]
	v_mfma_f32_16x16x32_bf16 v[82:85], v[198:201], v[222:225], v[82:85]
	v_mfma_f32_16x16x32_bf16 v[70:73], v[178:181], v[234:237], v[70:73]
	v_mfma_f32_16x16x32_bf16 v[66:69], v[198:201], v[234:237], v[66:69]
	s_barrier
	s_setprio 0
	s_add_i32 s52, s52, s41
	s_mov_b32 m0, s52
	ds_read_b128 v[202:205], v154 offset:16384
	global_load_lds_dwordx4 v0, vcc
	s_add_i32 m0, s52, 0x2000
	s_add_i32 s52, s53, s41
	ds_read_b128 v[206:209], v154 offset:17408
	global_load_lds_dwordx4 v134, vcc
	s_add_u32 vcc_lo, vcc_lo, s23
	s_addc_u32 vcc_hi, vcc_hi, 0
	s_mov_b32 m0, s52
	ds_read_b128 v[210:213], v154 offset:18432
	global_load_lds_dwordx4 v0, vcc
	s_add_i32 m0, s52, 0x2000
	ds_read_b128 v[214:217], v154 offset:19456
	global_load_lds_dwordx4 v134, vcc
	s_mov_b32 m0, s30
	ds_read_b128 v[218:221], v154 offset:20480
	global_load_lds_dwordx4 v130, s[26:27]
	s_mov_b32 m0, s31
	ds_read_b128 v[222:225], v154 offset:21504
	global_load_lds_dwordx4 v132, s[26:27]
	ds_read_b128 v[226:229], v154 offset:22528
	ds_read_b128 v[234:237], v154 offset:23552
	s_waitcnt vmcnt(8)
	s_waitcnt lgkmcnt(0)
	s_setprio 1
	s_barrier
	v_mfma_f32_16x16x32_bf16 v[62:65], v[140:143], v[202:205], v[62:65]
	v_mfma_f32_16x16x32_bf16 v[58:61], v[166:169], v[202:205], v[58:61]
	v_mfma_f32_16x16x32_bf16 v[46:49], v[140:143], v[210:213], v[46:49]
	v_mfma_f32_16x16x32_bf16 v[42:45], v[166:169], v[210:213], v[42:45]
	v_mfma_f32_16x16x32_bf16 v[30:33], v[140:143], v[218:221], v[30:33]
	v_mfma_f32_16x16x32_bf16 v[26:29], v[166:169], v[218:221], v[26:29]
	v_mfma_f32_16x16x32_bf16 v[14:17], v[140:143], v[226:229], v[14:17]
	v_mfma_f32_16x16x32_bf16 v[10:13], v[166:169], v[226:229], v[10:13]
	v_mfma_f32_16x16x32_bf16 v[62:65], v[156:159], v[206:209], v[62:65]
	v_mfma_f32_16x16x32_bf16 v[58:61], v[170:173], v[206:209], v[58:61]
	v_mfma_f32_16x16x32_bf16 v[46:49], v[156:159], v[214:217], v[46:49]
	v_mfma_f32_16x16x32_bf16 v[42:45], v[170:173], v[214:217], v[42:45]
	v_mfma_f32_16x16x32_bf16 v[30:33], v[156:159], v[222:225], v[30:33]
	v_mfma_f32_16x16x32_bf16 v[26:29], v[170:173], v[222:225], v[26:29]
	v_mfma_f32_16x16x32_bf16 v[14:17], v[156:159], v[234:237], v[14:17]
	v_mfma_f32_16x16x32_bf16 v[10:13], v[170:173], v[234:237], v[10:13]
	v_mfma_f32_16x16x32_bf16 v[54:57], v[174:177], v[202:205], v[54:57]
	v_mfma_f32_16x16x32_bf16 v[50:53], v[194:197], v[202:205], v[50:53]
	v_mfma_f32_16x16x32_bf16 v[38:41], v[174:177], v[210:213], v[38:41]
	v_mfma_f32_16x16x32_bf16 v[34:37], v[194:197], v[210:213], v[34:37]
	v_mfma_f32_16x16x32_bf16 v[22:25], v[174:177], v[218:221], v[22:25]
	v_mfma_f32_16x16x32_bf16 v[18:21], v[194:197], v[218:221], v[18:21]
	v_mfma_f32_16x16x32_bf16 v[6:9], v[174:177], v[226:229], v[6:9]
	v_mfma_f32_16x16x32_bf16 v[2:5], v[194:197], v[226:229], v[2:5]
	v_mfma_f32_16x16x32_bf16 v[54:57], v[178:181], v[206:209], v[54:57]
	v_mfma_f32_16x16x32_bf16 v[50:53], v[198:201], v[206:209], v[50:53]
	v_mfma_f32_16x16x32_bf16 v[38:41], v[178:181], v[214:217], v[38:41]
	v_mfma_f32_16x16x32_bf16 v[34:37], v[198:201], v[214:217], v[34:37]
	v_mfma_f32_16x16x32_bf16 v[22:25], v[178:181], v[222:225], v[22:25]
	v_mfma_f32_16x16x32_bf16 v[18:21], v[198:201], v[222:225], v[18:21]
	v_mfma_f32_16x16x32_bf16 v[6:9], v[178:181], v[234:237], v[6:9]
	v_mfma_f32_16x16x32_bf16 v[2:5], v[198:201], v[234:237], v[2:5]
	s_barrier
; #define PG8_STAGE(bufoff, gbase, voff) do { _Pragma("unroll") for (int _i = 0; _i < 2; ++_i) \
;         __builtin_amdgcn_global_load_lds((const unsigned*)((const char*)(gbase) + (voff)[_i]), (LAS unsigned*)(lds + (bufoff) + ldsw + _i * 8192), 16, 0, 0); } while (0)
; #define PG8_LDA(dst, b, h) do { _Pragma("unroll") for (int m = 0; m < 4; ++m) _Pragma("unroll") for (int k = 0; k < 2; ++k) dst[m][k] = *(const LAS bf16x8*)(lds + PG8_SA(b, h) + aoff + m * 2048 + k * 1024); } while (0)
; #define PG8_LDB(dst, b, h) do { _Pragma("unroll") for (int n = 0; n < 2; ++n) _Pragma("unroll") for (int k = 0; k < 2; ++k) dst[n][k] = *(const LAS bf16x8*)(lds + PG8_SB(b, h) + boff + n * 2048 + k * 1024); } while (0)
; #define PG8_MMA(ai, bj, At, Bt) do { __builtin_amdgcn_s_setprio(1); _Pragma("unroll") for (int m = 0; m < 4; ++m) _Pragma("unroll") for (int n = 0; n < 2; ++n) _Pragma("unroll") for (int k = 0; k < 2; ++k) \
;         acc[ai][bj][m][n] = __builtin_amdgcn_mfma_f32_16x16x32_bf16(Bt[n][k], At[m][k], acc[ai][bj][m][n], 0, 0, 0); __builtin_amdgcn_s_setprio(0); } while (0)
; #define PG8_WAIT_V(n) asm volatile("s_waitcnt vmcnt(" #n ")" ::: "memory")
; #define PG8_WAIT_L(n) asm volatile("s_waitcnt lgkmcnt(" #n ")" ::: "memory")
; #define PG8_BAR __builtin_amdgcn_s_barrier()
; #define PG8_SCHED __builtin_amdgcn_sched_barrier(0)
; template <class Epi>
; __device__ __forceinline__ void gemm_phase(LAS unsigned char* lds, const Gemm g, const StaticOrder& S, const Epi& E) {
;     ...
;             PG8_LDB(B0, 1, 0); PG8_LDB(B1, 1, 1); PG8_SCHED; PG8_LDA(At, 1, 0); PG8_STAGE(PG8_SA(0, 1), a2 + hstepA, voffA);
;             PG8_WAIT_V(8); PG8_WAIT_L(0); PG8_BAR; PG8_MMA(0, 0, At, B0); PG8_MMA(0, 1, At, B1); PG8_BAR; PG8_SCHED;
;             PG8_LDA(At, 1, 1); PG8_STAGE(PG8_SB(1, 0), b3, voffB); PG8_STAGE(PG8_SB(1, 1), b3 + hstepB, voffB); PG8_STAGE(PG8_SA(1, 0), a3, voffA);
;             PG8_WAIT_V(8); PG8_WAIT_L(0); PG8_BAR; PG8_MMA(1, 0, At, B0); PG8_MMA(1, 1, At, B1); PG8_BAR; PG8_SCHED;
;         }
;         if (wr == 0) PG8_BAR;
	s_setprio 0
	s_add_i32 s52, 0, 0x18000
	v_add_u32_e32 v155, s52, v145
	s_add_i32 s53, 0, 0x1c000
	ds_read_b128 v[140:143], v155
	ds_read_b128 v[156:159], v155 offset:1024
	ds_read_b128 v[166:169], v155 offset:2048
	ds_read_b128 v[170:173], v155 offset:3072
	v_add_u32_e32 v155, s53, v145
	ds_read_b128 v[174:177], v155
	ds_read_b128 v[178:181], v155 offset:1024
	ds_read_b128 v[194:197], v155 offset:2048
	ds_read_b128 v[198:201], v155 offset:3072
	s_add_u32 s26, s26, s78
	s_addc_u32 s27, s27, 0
	s_mov_b32 m0, s64
	ds_read_b128 v[202:205], v154 offset:32768
	global_load_lds_dwordx4 v130, s[26:27]
	s_mov_b32 m0, s85
	ds_read_b128 v[206:209], v154 offset:33792
	global_load_lds_dwordx4 v132, s[26:27]
	ds_read_b128 v[210:213], v154 offset:34816
	ds_read_b128 v[214:217], v154 offset:35840
	ds_read_b128 v[218:221], v154 offset:36864
	ds_read_b128 v[222:225], v154 offset:37888
	ds_read_b128 v[226:229], v154 offset:38912
	ds_read_b128 v[234:237], v154 offset:39936
	s_waitcnt vmcnt(8)
	s_waitcnt lgkmcnt(0)
	s_setprio 1
	s_barrier
	v_mfma_f32_16x16x32_bf16 v[126:129], v[140:143], v[202:205], v[126:129]
	v_mfma_f32_16x16x32_bf16 v[122:125], v[166:169], v[202:205], v[122:125]
	v_mfma_f32_16x16x32_bf16 v[110:113], v[140:143], v[210:213], v[110:113]
	v_mfma_f32_16x16x32_bf16 v[106:109], v[166:169], v[210:213], v[106:109]
	v_mfma_f32_16x16x32_bf16 v[94:97], v[140:143], v[218:221], v[94:97]
	v_mfma_f32_16x16x32_bf16 v[90:93], v[166:169], v[218:221], v[90:93]
	v_mfma_f32_16x16x32_bf16 v[78:81], v[140:143], v[226:229], v[78:81]
	v_mfma_f32_16x16x32_bf16 v[74:77], v[166:169], v[226:229], v[74:77]
	v_mfma_f32_16x16x32_bf16 v[126:129], v[156:159], v[206:209], v[126:129]
	v_mfma_f32_16x16x32_bf16 v[122:125], v[170:173], v[206:209], v[122:125]
	v_mfma_f32_16x16x32_bf16 v[110:113], v[156:159], v[214:217], v[110:113]
	v_mfma_f32_16x16x32_bf16 v[106:109], v[170:173], v[214:217], v[106:109]
	v_mfma_f32_16x16x32_bf16 v[94:97], v[156:159], v[222:225], v[94:97]
	v_mfma_f32_16x16x32_bf16 v[90:93], v[170:173], v[222:225], v[90:93]
	v_mfma_f32_16x16x32_bf16 v[78:81], v[156:159], v[234:237], v[78:81]
	v_mfma_f32_16x16x32_bf16 v[74:77], v[170:173], v[234:237], v[74:77]
	v_mfma_f32_16x16x32_bf16 v[118:121], v[174:177], v[202:205], v[118:121]
	v_mfma_f32_16x16x32_bf16 v[114:117], v[194:197], v[202:205], v[114:117]
	v_mfma_f32_16x16x32_bf16 v[102:105], v[174:177], v[210:213], v[102:105]
	v_mfma_f32_16x16x32_bf16 v[98:101], v[194:197], v[210:213], v[98:101]
	v_mfma_f32_16x16x32_bf16 v[86:89], v[174:177], v[218:221], v[86:89]
	v_mfma_f32_16x16x32_bf16 v[82:85], v[194:197], v[218:221], v[82:85]
	v_mfma_f32_16x16x32_bf16 v[70:73], v[174:177], v[226:229], v[70:73]
	v_mfma_f32_16x16x32_bf16 v[66:69], v[194:197], v[226:229], v[66:69]
	v_mfma_f32_16x16x32_bf16 v[118:121], v[178:181], v[206:209], v[118:121]
	v_mfma_f32_16x16x32_bf16 v[114:117], v[198:201], v[206:209], v[114:117]
	v_mfma_f32_16x16x32_bf16 v[102:105], v[178:181], v[214:217], v[102:105]
	v_mfma_f32_16x16x32_bf16 v[98:101], v[198:201], v[214:217], v[98:101]
	v_mfma_f32_16x16x32_bf16 v[86:89], v[178:181], v[222:225], v[86:89]
	v_mfma_f32_16x16x32_bf16 v[82:85], v[198:201], v[222:225], v[82:85]
	v_mfma_f32_16x16x32_bf16 v[70:73], v[178:181], v[234:237], v[70:73]
	v_mfma_f32_16x16x32_bf16 v[66:69], v[198:201], v[234:237], v[66:69]
	s_barrier
	s_setprio 0
	s_add_i32 s32, s52, s41
	s_sub_u32 vcc_lo, vcc_lo, s23
	s_subb_u32 vcc_hi, vcc_hi, 0
	s_add_u32 vcc_lo, vcc_lo, 0x80
	s_addc_u32 vcc_hi, vcc_hi, 0
	s_mov_b32 m0, s32
	ds_read_b128 v[202:205], v154 offset:49152
	global_load_lds_dwordx4 v0, vcc
	s_add_i32 m0, s32, 0x2000
	s_add_i32 s32, s53, s41
	ds_read_b128 v[206:209], v154 offset:50176
	global_load_lds_dwordx4 v134, vcc
	s_add_u32 vcc_lo, vcc_lo, s23
	s_addc_u32 vcc_hi, vcc_hi, 0
	s_mov_b32 m0, s32
	ds_read_b128 v[210:213], v154 offset:51200
	global_load_lds_dwordx4 v0, vcc
	s_add_i32 m0, s32, 0x2000
	s_sub_u32 s26, s26, s78
	s_subb_u32 s27, s27, 0
	ds_read_b128 v[214:217], v154 offset:52224
	global_load_lds_dwordx4 v134, vcc
	s_add_u32 s26, s26, 0x80
	s_addc_u32 s27, s27, 0
	s_mov_b32 m0, s92
	ds_read_b128 v[218:221], v154 offset:53248
	global_load_lds_dwordx4 v130, s[26:27]
	s_mov_b32 m0, s93
	ds_read_b128 v[222:225], v154 offset:54272
	global_load_lds_dwordx4 v132, s[26:27]
	ds_read_b128 v[226:229], v154 offset:55296
	ds_read_b128 v[234:237], v154 offset:56320
	s_waitcnt vmcnt(8)
	s_waitcnt lgkmcnt(0)
	s_setprio 1
	s_barrier
	v_mfma_f32_16x16x32_bf16 v[62:65], v[140:143], v[202:205], v[62:65]
	v_mfma_f32_16x16x32_bf16 v[58:61], v[166:169], v[202:205], v[58:61]
	v_mfma_f32_16x16x32_bf16 v[46:49], v[140:143], v[210:213], v[46:49]
	v_mfma_f32_16x16x32_bf16 v[42:45], v[166:169], v[210:213], v[42:45]
	v_mfma_f32_16x16x32_bf16 v[30:33], v[140:143], v[218:221], v[30:33]
	v_mfma_f32_16x16x32_bf16 v[26:29], v[166:169], v[218:221], v[26:29]
	v_mfma_f32_16x16x32_bf16 v[14:17], v[140:143], v[226:229], v[14:17]
	v_mfma_f32_16x16x32_bf16 v[10:13], v[166:169], v[226:229], v[10:13]
	v_mfma_f32_16x16x32_bf16 v[62:65], v[156:159], v[206:209], v[62:65]
	v_mfma_f32_16x16x32_bf16 v[58:61], v[170:173], v[206:209], v[58:61]
	v_mfma_f32_16x16x32_bf16 v[46:49], v[156:159], v[214:217], v[46:49]
	v_mfma_f32_16x16x32_bf16 v[42:45], v[170:173], v[214:217], v[42:45]
	v_mfma_f32_16x16x32_bf16 v[30:33], v[156:159], v[222:225], v[30:33]
	v_mfma_f32_16x16x32_bf16 v[26:29], v[170:173], v[222:225], v[26:29]
	v_mfma_f32_16x16x32_bf16 v[14:17], v[156:159], v[234:237], v[14:17]
	v_mfma_f32_16x16x32_bf16 v[10:13], v[170:173], v[234:237], v[10:13]
	v_mfma_f32_16x16x32_bf16 v[54:57], v[174:177], v[202:205], v[54:57]
	v_mfma_f32_16x16x32_bf16 v[50:53], v[194:197], v[202:205], v[50:53]
	v_mfma_f32_16x16x32_bf16 v[38:41], v[174:177], v[210:213], v[38:41]
	v_mfma_f32_16x16x32_bf16 v[34:37], v[194:197], v[210:213], v[34:37]
	v_mfma_f32_16x16x32_bf16 v[22:25], v[174:177], v[218:221], v[22:25]
	v_mfma_f32_16x16x32_bf16 v[18:21], v[194:197], v[218:221], v[18:21]
	v_mfma_f32_16x16x32_bf16 v[6:9], v[174:177], v[226:229], v[6:9]
	v_mfma_f32_16x16x32_bf16 v[2:5], v[194:197], v[226:229], v[2:5]
	v_mfma_f32_16x16x32_bf16 v[54:57], v[178:181], v[206:209], v[54:57]
	v_mfma_f32_16x16x32_bf16 v[50:53], v[198:201], v[206:209], v[50:53]
	v_mfma_f32_16x16x32_bf16 v[38:41], v[178:181], v[214:217], v[38:41]
	v_mfma_f32_16x16x32_bf16 v[34:37], v[198:201], v[214:217], v[34:37]
	v_mfma_f32_16x16x32_bf16 v[22:25], v[178:181], v[222:225], v[22:25]
	v_mfma_f32_16x16x32_bf16 v[18:21], v[198:201], v[222:225], v[18:21]
	v_mfma_f32_16x16x32_bf16 v[6:9], v[178:181], v[234:237], v[6:9]
	v_mfma_f32_16x16x32_bf16 v[2:5], v[198:201], v[234:237], v[2:5]
	s_barrier
	s_setprio 0
	s_add_u32 s12, s12, 0x100
	s_addc_u32 s13, s13, 0
	s_add_u32 s57, s57, 0x100
	s_addc_u32 s82, s82, 0
	s_cmp_ge_u32 s83, s80
	s_mov_b32 s26, s83
	s_cbranch_scc0 .LBB0_233
	s_and_b64 vcc, exec, s[74:75]
	s_cbranch_vccz .LBB0_236
	s_barrier

; #define PG8_STAGE(bufoff, gbase, voff) do { _Pragma("unroll") for (int _i = 0; _i < 2; ++_i) \
;         __builtin_amdgcn_global_load_lds((const unsigned*)((const char*)(gbase) + (voff)[_i]), (LAS unsigned*)(lds + (bufoff) + ldsw + _i * 8192), 16, 0, 0); } while (0)
; #define PG8_LDA(dst, b, h) do { _Pragma("unroll") for (int m = 0; m < 4; ++m) _Pragma("unroll") for (int k = 0; k < 2; ++k) dst[m][k] = *(const LAS bf16x8*)(lds + PG8_SA(b, h) + aoff + m * 2048 + k * 1024); } while (0)
; #define PG8_LDB(dst, b, h) do { _Pragma("unroll") for (int n = 0; n < 2; ++n) _Pragma("unroll") for (int k = 0; k < 2; ++k) dst[n][k] = *(const LAS bf16x8*)(lds + PG8_SB(b, h) + boff + n * 2048 + k * 1024); } while (0)
; #define PG8_MMA(ai, bj, At, Bt) do { __builtin_amdgcn_s_setprio(1); _Pragma("unroll") for (int m = 0; m < 4; ++m) _Pragma("unroll") for (int n = 0; n < 2; ++n) _Pragma("unroll") for (int k = 0; k < 2; ++k) \
;         acc[ai][bj][m][n] = __builtin_amdgcn_mfma_f32_16x16x32_bf16(Bt[n][k], At[m][k], acc[ai][bj][m][n], 0, 0, 0); __builtin_amdgcn_s_setprio(0); } while (0)
; #define PG8_WAIT_V(n) asm volatile("s_waitcnt vmcnt(" #n ")" ::: "memory")
; #define PG8_WAIT_L(n) asm volatile("s_waitcnt lgkmcnt(" #n ")" ::: "memory")
; #define PG8_BAR __builtin_amdgcn_s_barrier()
; #define PG8_SCHED __builtin_amdgcn_sched_barrier(0)
; template <class Epi>
; __device__ __forceinline__ void gemm_phase(LAS unsigned char* lds, const Gemm g, const StaticOrder& S, const Epi& E) {
;     ...
;         for (int t = 0; t < nt; t += 2) {
;             const bool last = (t == nt - 2);
;             const char* a1 = cA + (size_t)(t + 1) * kstep;
;             const char* a2 = last ? nA : cA + (size_t)(t + 2) * kstep; const char* b2 = last ? nB : cB + (size_t)(t + 2) * kstep;
;             const char* a3 = a2 + kstep; const char* b3 = b2 + kstep;
;             PG8_LDB(B0, 0, 0); PG8_LDB(B1, 0, 1); PG8_SCHED; PG8_LDA(At, 0, 0); PG8_STAGE(PG8_SA(1, 1), a1 + hstepA, voffA);
;             PG8_WAIT_V(8); PG8_WAIT_L(0); PG8_BAR; PG8_MMA(0, 0, At, B0); PG8_MMA(0, 1, At, B1); PG8_BAR; PG8_SCHED;
;             PG8_LDA(At, 0, 1); PG8_STAGE(PG8_SB(0, 0), b2, voffB); PG8_STAGE(PG8_SB(0, 1), b2 + hstepB, voffB); PG8_STAGE(PG8_SA(0, 0), a2, voffA);
;             PG8_WAIT_V(8); PG8_WAIT_L(0); PG8_BAR; PG8_MMA(1, 0, At, B0); PG8_MMA(1, 1, At, B1); PG8_BAR; PG8_SCHED;
.LBB0_295:
	s_add_i32 s50, 0, 0x10000
	s_add_i32 s56, 0, 0x14000
	v_add_u32_e32 v156, s50, v145
	v_add_u32_e32 v160, s56, v145
	ds_read_b128 v[140:143], v156
	ds_read_b128 v[148:151], v156 offset:1024
	ds_read_b128 v[152:155], v156 offset:2048
	ds_read_b128 v[156:159], v156 offset:3072
	ds_read_b128 v[166:169], v160
	ds_read_b128 v[170:173], v160 offset:1024
	ds_read_b128 v[174:177], v160 offset:2048
	ds_read_b128 v[178:181], v160 offset:3072
	s_add_u32 s26, s24, 0xfff80080
	s_addc_u32 s27, s25, -1
	s_cmp_eq_u32 s49, 28
	s_cselect_b32 s35, s13, s27
	s_cselect_b32 s34, s43, s26
	s_cselect_b32 s27, s11, s48
	s_cselect_b32 s26, s46, s47
	s_add_i32 m0, s19, 0xc000
	ds_read_b128 v[194:197], v147
	global_load_lds_dwordx4 v136, s[24:25]
	s_add_i32 m0, s19, 0xe000
	ds_read_b128 v[198:201], v147 offset:1024
	global_load_lds_dwordx4 v138, s[24:25]
	ds_read_b128 v[202:205], v147 offset:2048
	ds_read_b128 v[206:209], v147 offset:3072
	ds_read_b128 v[210:213], v147 offset:4096
	ds_read_b128 v[214:217], v147 offset:5120
	ds_read_b128 v[218:221], v147 offset:6144
	ds_read_b128 v[222:225], v147 offset:7168
	s_waitcnt vmcnt(8)
	s_waitcnt lgkmcnt(0)
	s_setprio 1
	s_barrier
	v_mfma_f32_16x16x32_bf16 v[126:129], v[140:143], v[194:197], v[126:129]
	v_mfma_f32_16x16x32_bf16 v[122:125], v[152:155], v[194:197], v[122:125]
	v_mfma_f32_16x16x32_bf16 v[110:113], v[140:143], v[202:205], v[110:113]
	v_mfma_f32_16x16x32_bf16 v[106:109], v[152:155], v[202:205], v[106:109]
	v_mfma_f32_16x16x32_bf16 v[94:97], v[140:143], v[210:213], v[94:97]
	v_mfma_f32_16x16x32_bf16 v[90:93], v[152:155], v[210:213], v[90:93]
	v_mfma_f32_16x16x32_bf16 v[78:81], v[140:143], v[218:221], v[78:81]
	v_mfma_f32_16x16x32_bf16 v[74:77], v[152:155], v[218:221], v[74:77]
	v_mfma_f32_16x16x32_bf16 v[126:129], v[148:151], v[198:201], v[126:129]
	v_mfma_f32_16x16x32_bf16 v[122:125], v[156:159], v[198:201], v[122:125]
	v_mfma_f32_16x16x32_bf16 v[110:113], v[148:151], v[206:209], v[110:113]
	v_mfma_f32_16x16x32_bf16 v[106:109], v[156:159], v[206:209], v[106:109]
	v_mfma_f32_16x16x32_bf16 v[94:97], v[148:151], v[214:217], v[94:97]
	v_mfma_f32_16x16x32_bf16 v[90:93], v[156:159], v[214:217], v[90:93]
	v_mfma_f32_16x16x32_bf16 v[78:81], v[148:151], v[222:225], v[78:81]
	v_mfma_f32_16x16x32_bf16 v[74:77], v[156:159], v[222:225], v[74:77]
	v_mfma_f32_16x16x32_bf16 v[118:121], v[166:169], v[194:197], v[118:121]
	v_mfma_f32_16x16x32_bf16 v[114:117], v[174:177], v[194:197], v[114:117]
	v_mfma_f32_16x16x32_bf16 v[102:105], v[166:169], v[202:205], v[102:105]
	v_mfma_f32_16x16x32_bf16 v[98:101], v[174:177], v[202:205], v[98:101]
	v_mfma_f32_16x16x32_bf16 v[86:89], v[166:169], v[210:213], v[86:89]
	v_mfma_f32_16x16x32_bf16 v[82:85], v[174:177], v[210:213], v[82:85]
	v_mfma_f32_16x16x32_bf16 v[70:73], v[166:169], v[218:221], v[70:73]
	v_mfma_f32_16x16x32_bf16 v[66:69], v[174:177], v[218:221], v[66:69]
	v_mfma_f32_16x16x32_bf16 v[118:121], v[170:173], v[198:201], v[118:121]
	v_mfma_f32_16x16x32_bf16 v[114:117], v[178:181], v[198:201], v[114:117]
	v_mfma_f32_16x16x32_bf16 v[102:105], v[170:173], v[206:209], v[102:105]
	v_mfma_f32_16x16x32_bf16 v[98:101], v[178:181], v[206:209], v[98:101]
	v_mfma_f32_16x16x32_bf16 v[86:89], v[170:173], v[214:217], v[86:89]
	v_mfma_f32_16x16x32_bf16 v[82:85], v[178:181], v[214:217], v[82:85]
	v_mfma_f32_16x16x32_bf16 v[70:73], v[170:173], v[222:225], v[70:73]
	v_mfma_f32_16x16x32_bf16 v[66:69], v[178:181], v[222:225], v[66:69]
	s_barrier
	s_setprio 0
	s_add_i32 s50, s50, s23
	s_mov_b32 m0, s50
	ds_read_b128 v[194:197], v147 offset:16384
	global_load_lds_dwordx4 v0, s[26:27]
	s_add_i32 m0, s50, 0x2000
	s_add_u32 s50, s26, 0x80000
	s_addc_u32 s51, s27, 0
	s_add_i32 s56, s56, s23
	ds_read_b128 v[198:201], v147 offset:17408
	global_load_lds_dwordx4 v130, s[26:27]
	s_mov_b32 m0, s56
	ds_read_b128 v[202:205], v147 offset:18432
	global_load_lds_dwordx4 v0, s[50:51]
	s_add_i32 m0, s56, 0x2000
	ds_read_b128 v[206:209], v147 offset:19456
	global_load_lds_dwordx4 v130, s[50:51]
	s_mov_b32 m0, s19
	ds_read_b128 v[210:213], v147 offset:20480
	global_load_lds_dwordx4 v134, s[34:35]
	s_mov_b32 m0, s31
	ds_read_b128 v[214:217], v147 offset:21504
	global_load_lds_dwordx4 v132, s[34:35]
	ds_read_b128 v[218:221], v147 offset:22528
	ds_read_b128 v[222:225], v147 offset:23552
	s_waitcnt vmcnt(8)
	s_waitcnt lgkmcnt(0)
	s_setprio 1
	s_barrier
	v_mfma_f32_16x16x32_bf16 v[62:65], v[140:143], v[194:197], v[62:65]
	v_mfma_f32_16x16x32_bf16 v[58:61], v[152:155], v[194:197], v[58:61]
	v_mfma_f32_16x16x32_bf16 v[46:49], v[140:143], v[202:205], v[46:49]
	v_mfma_f32_16x16x32_bf16 v[42:45], v[152:155], v[202:205], v[42:45]
	v_mfma_f32_16x16x32_bf16 v[30:33], v[140:143], v[210:213], v[30:33]
	v_mfma_f32_16x16x32_bf16 v[26:29], v[152:155], v[210:213], v[26:29]
	v_mfma_f32_16x16x32_bf16 v[14:17], v[140:143], v[218:221], v[14:17]
	v_mfma_f32_16x16x32_bf16 v[10:13], v[152:155], v[218:221], v[10:13]
	v_mfma_f32_16x16x32_bf16 v[62:65], v[148:151], v[198:201], v[62:65]
	v_mfma_f32_16x16x32_bf16 v[58:61], v[156:159], v[198:201], v[58:61]
	v_mfma_f32_16x16x32_bf16 v[46:49], v[148:151], v[206:209], v[46:49]
	v_mfma_f32_16x16x32_bf16 v[42:45], v[156:159], v[206:209], v[42:45]
	v_mfma_f32_16x16x32_bf16 v[30:33], v[148:151], v[214:217], v[30:33]
	v_mfma_f32_16x16x32_bf16 v[26:29], v[156:159], v[214:217], v[26:29]
	v_mfma_f32_16x16x32_bf16 v[14:17], v[148:151], v[222:225], v[14:17]
	v_mfma_f32_16x16x32_bf16 v[10:13], v[156:159], v[222:225], v[10:13]
	v_mfma_f32_16x16x32_bf16 v[54:57], v[166:169], v[194:197], v[54:57]
	v_mfma_f32_16x16x32_bf16 v[50:53], v[174:177], v[194:197], v[50:53]
	v_mfma_f32_16x16x32_bf16 v[38:41], v[166:169], v[202:205], v[38:41]
	v_mfma_f32_16x16x32_bf16 v[34:37], v[174:177], v[202:205], v[34:37]
	v_mfma_f32_16x16x32_bf16 v[22:25], v[166:169], v[210:213], v[22:25]
	v_mfma_f32_16x16x32_bf16 v[18:21], v[174:177], v[210:213], v[18:21]
	v_mfma_f32_16x16x32_bf16 v[6:9], v[166:169], v[218:221], v[6:9]
	v_mfma_f32_16x16x32_bf16 v[2:5], v[174:177], v[218:221], v[2:5]
	v_mfma_f32_16x16x32_bf16 v[54:57], v[170:173], v[198:201], v[54:57]
	v_mfma_f32_16x16x32_bf16 v[50:53], v[178:181], v[198:201], v[50:53]
	v_mfma_f32_16x16x32_bf16 v[38:41], v[170:173], v[206:209], v[38:41]
	v_mfma_f32_16x16x32_bf16 v[34:37], v[178:181], v[206:209], v[34:37]
	v_mfma_f32_16x16x32_bf16 v[22:25], v[170:173], v[214:217], v[22:25]
	v_mfma_f32_16x16x32_bf16 v[18:21], v[178:181], v[214:217], v[18:21]
	v_mfma_f32_16x16x32_bf16 v[6:9], v[170:173], v[222:225], v[6:9]
	v_mfma_f32_16x16x32_bf16 v[2:5], v[178:181], v[222:225], v[2:5]
	s_barrier
; #define PG8_STAGE(bufoff, gbase, voff) do { _Pragma("unroll") for (int _i = 0; _i < 2; ++_i) \
;         __builtin_amdgcn_global_load_lds((const unsigned*)((const char*)(gbase) + (voff)[_i]), (LAS unsigned*)(lds + (bufoff) + ldsw + _i * 8192), 16, 0, 0); } while (0)
; #define PG8_LDA(dst, b, h) do { _Pragma("unroll") for (int m = 0; m < 4; ++m) _Pragma("unroll") for (int k = 0; k < 2; ++k) dst[m][k] = *(const LAS bf16x8*)(lds + PG8_SA(b, h) + aoff + m * 2048 + k * 1024); } while (0)
; #define PG8_LDB(dst, b, h) do { _Pragma("unroll") for (int n = 0; n < 2; ++n) _Pragma("unroll") for (int k = 0; k < 2; ++k) dst[n][k] = *(const LAS bf16x8*)(lds + PG8_SB(b, h) + boff + n * 2048 + k * 1024); } while (0)
; #define PG8_MMA(ai, bj, At, Bt) do { __builtin_amdgcn_s_setprio(1); _Pragma("unroll") for (int m = 0; m < 4; ++m) _Pragma("unroll") for (int n = 0; n < 2; ++n) _Pragma("unroll") for (int k = 0; k < 2; ++k) \
;         acc[ai][bj][m][n] = __builtin_amdgcn_mfma_f32_16x16x32_bf16(Bt[n][k], At[m][k], acc[ai][bj][m][n], 0, 0, 0); __builtin_amdgcn_s_setprio(0); } while (0)
; #define PG8_WAIT_V(n) asm volatile("s_waitcnt vmcnt(" #n ")" ::: "memory")
; #define PG8_WAIT_L(n) asm volatile("s_waitcnt lgkmcnt(" #n ")" ::: "memory")
; #define PG8_BAR __builtin_amdgcn_s_barrier()
; #define PG8_SCHED __builtin_amdgcn_sched_barrier(0)
; template <class Epi>
; __device__ __forceinline__ void gemm_phase(LAS unsigned char* lds, const Gemm g, const StaticOrder& S, const Epi& E) {
;     ...
;             PG8_LDB(B0, 1, 0); PG8_LDB(B1, 1, 1); PG8_SCHED; PG8_LDA(At, 1, 0); PG8_STAGE(PG8_SA(0, 1), a2 + hstepA, voffA);
;             PG8_WAIT_V(8); PG8_WAIT_L(0); PG8_BAR; PG8_MMA(0, 0, At, B0); PG8_MMA(0, 1, At, B1); PG8_BAR; PG8_SCHED;
;             PG8_LDA(At, 1, 1); PG8_STAGE(PG8_SB(1, 0), b3, voffB); PG8_STAGE(PG8_SB(1, 1), b3 + hstepB, voffB); PG8_STAGE(PG8_SA(1, 0), a3, voffA);
;             PG8_WAIT_V(8); PG8_WAIT_L(0); PG8_BAR; PG8_MMA(1, 0, At, B0); PG8_MMA(1, 1, At, B1); PG8_BAR; PG8_SCHED;
;         }
;         if (wr == 0) PG8_BAR;
	s_setprio 0
	s_add_i32 s50, 0, 0x18000
	s_add_i32 s51, 0, 0x1c000
	v_add_u32_e32 v156, s50, v145
	v_add_u32_e32 v178, s51, v145
	ds_read_b128 v[140:143], v156
	ds_read_b128 v[148:151], v156 offset:1024
	ds_read_b128 v[152:155], v156 offset:2048
	ds_read_b128 v[156:159], v156 offset:3072
	ds_read_b128 v[166:169], v178
	ds_read_b128 v[170:173], v178 offset:1024
	ds_read_b128 v[174:177], v178 offset:2048
	ds_read_b128 v[178:181], v178 offset:3072
	s_add_u32 s34, s34, 0x80000
	s_addc_u32 s35, s35, 0
	s_mov_b32 m0, s36
	ds_read_b128 v[194:197], v147 offset:32768
	global_load_lds_dwordx4 v134, s[34:35]
	s_mov_b32 m0, s37
	ds_read_b128 v[198:201], v147 offset:33792
	global_load_lds_dwordx4 v132, s[34:35]
	ds_read_b128 v[202:205], v147 offset:34816
	ds_read_b128 v[206:209], v147 offset:35840
	ds_read_b128 v[210:213], v147 offset:36864
	ds_read_b128 v[214:217], v147 offset:37888
	ds_read_b128 v[218:221], v147 offset:38912
	ds_read_b128 v[222:225], v147 offset:39936
	s_waitcnt vmcnt(8)
	s_waitcnt lgkmcnt(0)
	s_setprio 1
	s_barrier
	v_mfma_f32_16x16x32_bf16 v[126:129], v[140:143], v[194:197], v[126:129]
	v_mfma_f32_16x16x32_bf16 v[122:125], v[152:155], v[194:197], v[122:125]
	v_mfma_f32_16x16x32_bf16 v[110:113], v[140:143], v[202:205], v[110:113]
	v_mfma_f32_16x16x32_bf16 v[106:109], v[152:155], v[202:205], v[106:109]
	v_mfma_f32_16x16x32_bf16 v[94:97], v[140:143], v[210:213], v[94:97]
	v_mfma_f32_16x16x32_bf16 v[90:93], v[152:155], v[210:213], v[90:93]
	v_mfma_f32_16x16x32_bf16 v[78:81], v[140:143], v[218:221], v[78:81]
	v_mfma_f32_16x16x32_bf16 v[74:77], v[152:155], v[218:221], v[74:77]
	v_mfma_f32_16x16x32_bf16 v[126:129], v[148:151], v[198:201], v[126:129]
	v_mfma_f32_16x16x32_bf16 v[122:125], v[156:159], v[198:201], v[122:125]
	v_mfma_f32_16x16x32_bf16 v[110:113], v[148:151], v[206:209], v[110:113]
	v_mfma_f32_16x16x32_bf16 v[106:109], v[156:159], v[206:209], v[106:109]
	v_mfma_f32_16x16x32_bf16 v[94:97], v[148:151], v[214:217], v[94:97]
	v_mfma_f32_16x16x32_bf16 v[90:93], v[156:159], v[214:217], v[90:93]
	v_mfma_f32_16x16x32_bf16 v[78:81], v[148:151], v[222:225], v[78:81]
	v_mfma_f32_16x16x32_bf16 v[74:77], v[156:159], v[222:225], v[74:77]
	v_mfma_f32_16x16x32_bf16 v[118:121], v[166:169], v[194:197], v[118:121]
	v_mfma_f32_16x16x32_bf16 v[114:117], v[174:177], v[194:197], v[114:117]
	v_mfma_f32_16x16x32_bf16 v[102:105], v[166:169], v[202:205], v[102:105]
	v_mfma_f32_16x16x32_bf16 v[98:101], v[174:177], v[202:205], v[98:101]
	v_mfma_f32_16x16x32_bf16 v[86:89], v[166:169], v[210:213], v[86:89]
	v_mfma_f32_16x16x32_bf16 v[82:85], v[174:177], v[210:213], v[82:85]
	v_mfma_f32_16x16x32_bf16 v[70:73], v[166:169], v[218:221], v[70:73]
	v_mfma_f32_16x16x32_bf16 v[66:69], v[174:177], v[218:221], v[66:69]
	v_mfma_f32_16x16x32_bf16 v[118:121], v[170:173], v[198:201], v[118:121]
	v_mfma_f32_16x16x32_bf16 v[114:117], v[178:181], v[198:201], v[114:117]
	v_mfma_f32_16x16x32_bf16 v[102:105], v[170:173], v[206:209], v[102:105]
	v_mfma_f32_16x16x32_bf16 v[98:101], v[178:181], v[206:209], v[98:101]
	v_mfma_f32_16x16x32_bf16 v[86:89], v[170:173], v[214:217], v[86:89]
	v_mfma_f32_16x16x32_bf16 v[82:85], v[178:181], v[214:217], v[82:85]
	v_mfma_f32_16x16x32_bf16 v[70:73], v[170:173], v[222:225], v[70:73]
	v_mfma_f32_16x16x32_bf16 v[66:69], v[178:181], v[222:225], v[66:69]
	s_barrier
	s_setprio 0
	s_add_i32 s32, s50, s23
	s_add_u32 s26, s26, 0x80
	s_addc_u32 s27, s27, 0
	s_mov_b32 m0, s32
	ds_read_b128 v[194:197], v147 offset:49152
	global_load_lds_dwordx4 v0, s[26:27]
	s_add_i32 m0, s32, 0x2000
	s_add_i32 s32, s51, s23
	ds_read_b128 v[198:201], v147 offset:50176
	global_load_lds_dwordx4 v130, s[26:27]
	s_add_u32 s26, s26, 0x80000
	s_addc_u32 s27, s27, 0
	s_mov_b32 m0, s32
	ds_read_b128 v[202:205], v147 offset:51200
	global_load_lds_dwordx4 v0, s[26:27]
	s_add_i32 m0, s32, 0x2000
	s_sub_u32 s34, s34, 0x7ff80
	s_subb_u32 s35, s35, 0
	ds_read_b128 v[206:209], v147 offset:52224
	global_load_lds_dwordx4 v130, s[26:27]
	s_mov_b32 m0, s38
	ds_read_b128 v[210:213], v147 offset:53248
	global_load_lds_dwordx4 v134, s[34:35]
	s_mov_b32 m0, s39
	ds_read_b128 v[214:217], v147 offset:54272
	global_load_lds_dwordx4 v132, s[34:35]
	ds_read_b128 v[218:221], v147 offset:55296
	ds_read_b128 v[222:225], v147 offset:56320
	s_waitcnt vmcnt(8)
	s_waitcnt lgkmcnt(0)
	s_setprio 1
	s_barrier
	v_mfma_f32_16x16x32_bf16 v[62:65], v[140:143], v[194:197], v[62:65]
	v_mfma_f32_16x16x32_bf16 v[58:61], v[152:155], v[194:197], v[58:61]
	v_mfma_f32_16x16x32_bf16 v[46:49], v[140:143], v[202:205], v[46:49]
	v_mfma_f32_16x16x32_bf16 v[42:45], v[152:155], v[202:205], v[42:45]
	v_mfma_f32_16x16x32_bf16 v[30:33], v[140:143], v[210:213], v[30:33]
	v_mfma_f32_16x16x32_bf16 v[26:29], v[152:155], v[210:213], v[26:29]
	v_mfma_f32_16x16x32_bf16 v[14:17], v[140:143], v[218:221], v[14:17]
	v_mfma_f32_16x16x32_bf16 v[10:13], v[152:155], v[218:221], v[10:13]
	v_mfma_f32_16x16x32_bf16 v[62:65], v[148:151], v[198:201], v[62:65]
	v_mfma_f32_16x16x32_bf16 v[58:61], v[156:159], v[198:201], v[58:61]
	v_mfma_f32_16x16x32_bf16 v[46:49], v[148:151], v[206:209], v[46:49]
	v_mfma_f32_16x16x32_bf16 v[42:45], v[156:159], v[206:209], v[42:45]
	v_mfma_f32_16x16x32_bf16 v[30:33], v[148:151], v[214:217], v[30:33]
	v_mfma_f32_16x16x32_bf16 v[26:29], v[156:159], v[214:217], v[26:29]
	v_mfma_f32_16x16x32_bf16 v[14:17], v[148:151], v[222:225], v[14:17]
	v_mfma_f32_16x16x32_bf16 v[10:13], v[156:159], v[222:225], v[10:13]
	v_mfma_f32_16x16x32_bf16 v[54:57], v[166:169], v[194:197], v[54:57]
	v_mfma_f32_16x16x32_bf16 v[50:53], v[174:177], v[194:197], v[50:53]
	v_mfma_f32_16x16x32_bf16 v[38:41], v[166:169], v[202:205], v[38:41]
	v_mfma_f32_16x16x32_bf16 v[34:37], v[174:177], v[202:205], v[34:37]
	v_mfma_f32_16x16x32_bf16 v[22:25], v[166:169], v[210:213], v[22:25]
	v_mfma_f32_16x16x32_bf16 v[18:21], v[174:177], v[210:213], v[18:21]
	v_mfma_f32_16x16x32_bf16 v[6:9], v[166:169], v[218:221], v[6:9]
	v_mfma_f32_16x16x32_bf16 v[2:5], v[174:177], v[218:221], v[2:5]
	v_mfma_f32_16x16x32_bf16 v[54:57], v[170:173], v[198:201], v[54:57]
	v_mfma_f32_16x16x32_bf16 v[50:53], v[178:181], v[198:201], v[50:53]
	v_mfma_f32_16x16x32_bf16 v[38:41], v[170:173], v[206:209], v[38:41]
	v_mfma_f32_16x16x32_bf16 v[34:37], v[178:181], v[206:209], v[34:37]
	v_mfma_f32_16x16x32_bf16 v[22:25], v[170:173], v[214:217], v[22:25]
	v_mfma_f32_16x16x32_bf16 v[18:21], v[178:181], v[214:217], v[18:21]
	v_mfma_f32_16x16x32_bf16 v[6:9], v[170:173], v[222:225], v[6:9]
	v_mfma_f32_16x16x32_bf16 v[2:5], v[178:181], v[222:225], v[2:5]
	s_barrier
	s_setprio 0
	s_add_i32 s49, s49, 2
	s_add_u32 s24, s24, 0x100
	s_addc_u32 s25, s25, 0
	s_add_u32 s47, s47, 0x100
	s_addc_u32 s48, s48, 0
	s_cmp_gt_u32 s49, 29
	s_cbranch_scc0 .LBB0_295
	s_and_b64 vcc, exec, s[8:9]
	s_cbranch_vccz .LBB0_298
	s_barrier
